# P2 top-k job order: batch 0's jobs then batch 1's (was alternating): one batch's indexer-key stream live in L2 at a time
# speedup vs baseline: 1.0042x; 1.0014x over previous
; __global__ void __launch_bounds__(NTHREADS) mega(Params p) {
;     ...
;         const int j = next_job(p.ctr + l * 2 + 8 * rep, lds, pending, NJ, par);
;         if (j >= NJ) break;
;         if (j < 16) {
;           cumsum_job(p, j, lds);
;         } else if (j < 16 + NTK) {
;           const int jj = j - 16;
;           const int b = jj & 1, q = 2051 - (jj >> 1);
;           topk_job(p, b, LEAD + 4 * q, lds);
.LBB0_618:
	s_sub_i32 s2, s87, 16
	s_cmpk_lt_u32 s2, 0x1008
	s_cbranch_scc0 .Ltks_a
	s_cmpk_lt_u32 s2, 0x804
	s_cselect_b32 s3, 0, 1
	s_cbranch_scc1 .Ltkb_a
	s_sub_i32 s2, s2, 0x804
.Ltkb_a:
	s_lshl_b32 s2, s2, 1
	s_add_i32 s2, s2, s3
	s_add_i32 s87, s2, 16

; DI int opaque_tid() { int t = threadIdx.x; asm volatile("" : "+v"(t)); return t; }
; DI int next_job(unsigned* ctr, char* lds, int& pending, int njobs, int& par) {
;   int* sj = (int*)(lds + LDS_JOB);
;   if (threadIdx.x == 0) sj[par] = pending;
;   __syncthreads();
;   const int j = sj[par];
;   par ^= 1;
;   if (threadIdx.x == 0 && j < njobs) pending = (int)atomicAdd(ctr, 1u);
;   return j;
; DI void topk_job(const Params& p, int b, int t0, char* lds) {
;   const int tid = opaque_tid(), lane = tid & 63, w = tid >> 6, r = lane & 31, h = lane >> 5;
;   const int cmax = (t0 + 3) >> 6;
;   unsigned sc[17][4];
;   {
;     const u16* iqp = p.H + (size_t)(b * PP + t0 + (r >> 3)) * LDH + HIQ_C + (r & 7) * 64 + 8 * h;
;     bf16x8 af[4];
; #pragma unroll
;     for (int ks = 0; ks < 4; ++ks) af[ks] = *(const bf16x8*)(iqp + ks * 16);
;     f32x4 iw[4];
; #pragma unroll
;     for (int qi = 0; qi < 4; ++qi) iw[qi] = *(const f32x4*)(p.IW + (size_t)(b * PP + t0 + qi) * 8 + 4 * h);
;     char* wb = lds + 16384 + w * 9216;
;     const int lrow = lane >> 3, lpc = lane & 7;
;     const u16* ikb = p.IK + ((size_t)(b * PP) + lrow) * 64 + lpc * 8;
;     u32x4 st[8];
;     if (1 + w <= cmax) {
;       const u16* kp = ikb + (size_t)(1 + w) * 64 * 64;
; #pragma unroll
;       for (int j = 0; j < 8; ++j) st[j] = *(const u32x4*)(kp + (size_t)j * 8 * 64);
; #pragma unroll
;       for (int j = 0; j < 8; ++j) *(u32x4*)(wb + (lrow + 8 * j) * 144 + lpc * 16) = st[j];
;     }
.Lsc_end:
	s_waitcnt vmcnt(0) lgkmcnt(0)
	v_lshrrev_b32_e32 v0, 6, v100
	s_mov_b32 s3, s90
	v_readfirstlane_b32 s2, v0
	s_lshl_b32 s4, s87, 1
	s_and_b32 s4, s4, 0x3ffc
	s_sub_i32 s4, 0x209c, s4
	s_bitcmp1_b32 s87, 0
	s_cselect_b32 s5, 0x2100, 0
	s_add_i32 s4, s4, s5
	v_readlane_b32 s6, v240, 13
	v_readlane_b32 s7, v240, 14
	s_lshl_b32 s5, s4, 9
	s_add_u32 s40, s6, s5
	s_addc_u32 s41, s7, 0
	s_add_u32 s42, s40, 0x200
	s_addc_u32 s43, s41, 0
	s_add_u32 s44, s42, 0x200
	s_addc_u32 s45, s43, 0
	s_add_u32 s46, s44, 0x200
	s_addc_u32 s47, s45, 0
	s_mov_b32 s16, 0x55555555
	s_mov_b32 s17, 0x55555555
	s_mov_b32 s18, 0x33333333
	s_mov_b32 s19, 0x33333333
	s_mov_b32 s20, 0xf0f0f0f
	s_mov_b32 s21, 0xf0f0f0f
	s_mov_b32 s22, 0xff00ff
	s_mov_b32 s23, 0xff00ff
	s_mov_b32 s24, 0xffff
	s_mov_b32 s25, 0xffff
	s_mov_b32 s26, 0xffffffff
	s_mov_b32 s27, 0
	v_mov_b32_e32 v20, 1
	v_and_b32_e32 v0, 3, v101
	v_lshlrev_b32_e32 v0, 12, v0
	v_add_u32_e32 v21, 0x4000, v0
	v_add_u32_e32 v25, 0x14000, v0
	v_mov_b32_e32 v29, 0x4000
	v_add_u32_e32 v22, 0x8000, v0
	v_add_u32_e32 v26, 0x18000, v0
	v_mov_b32_e32 v30, 0x8000
	v_add_u32_e32 v23, 0xc000, v0
	v_add_u32_e32 v27, 0x1c000, v0
	v_mov_b32_e32 v31, 0xc000
	v_add_u32_e32 v24, 0x10000, v0
	v_add_u32_e32 v28, 0x20000, v0
	v_mov_b32_e32 v32, 0x10000
	s_movk_i32 s85, 0x100
	s_mov_b32 s56, 0
	s_mov_b32 s58, 0
	v_cmp_eq_u32_e32 vcc, 0, v100
	s_and_saveexec_b64 s[30:31], vcc
	ds_write_b32 v3, v136 offset:768
	s_mov_b64 exec, s[30:31]
	s_waitcnt lgkmcnt(0)
	v_lshlrev_b32_e32 v75, 2, v100
	v_add_u32_e32 v75, 0x2800, v75
	v_lshlrev_b32_e32 v76, 1, v100
	v_add_u32_e32 v76, 0x800, v76
	s_barrier
	v_mov_b32_e32 v4, 0
	v_mov_b32_e32 v5, 0
	v_mov_b32_e32 v6, 0
	v_mov_b32_e32 v7, 0
	v_lshlrev_b32_e32 v0, 4, v100
	v_add_u32_e32 v0, 0x4000, v0
	v_add_u32_e32 v1, 0x10000, v0
	ds_write_b128 v0, v[4:7]
	ds_write_b128 v0, v[4:7] offset:8192
	ds_write_b128 v0, v[4:7] offset:16384
	ds_write_b128 v0, v[4:7] offset:24576
	ds_write_b128 v0, v[4:7] offset:32768
	ds_write_b128 v0, v[4:7] offset:40960
	ds_write_b128 v0, v[4:7] offset:49152
	ds_write_b128 v0, v[4:7] offset:57344
	v_mov_b32_e32 v2, -1
	v_lshlrev_b32_e32 v0, 2, v100
	ds_write_b32 v0, v2 offset:8192
	s_waitcnt lgkmcnt(0)
	s_barrier
	ds_read_b32 v0, v3 offset:768
	s_waitcnt lgkmcnt(0)
	v_readfirstlane_b32 s63, v0
	s_sub_i32 s4, s63, 16
	s_cmpk_lt_u32 s4, 0x1008
	s_cbranch_scc0 .Ltks_b
	s_cmpk_lt_u32 s4, 0x804
	s_cselect_b32 s5, 0, 1
	s_cbranch_scc1 .Ltkb_b
	s_sub_i32 s4, s4, 0x804
.Ltkb_b:
	s_lshl_b32 s4, s4, 1
	s_add_i32 s4, s4, s5
	s_add_i32 s63, s4, 16
.Ltks_b:
	s_cmp_lt_u32 s63, 16
	s_cbranch_scc1 .Ltk_pf_end_1
	s_cmpk_gt_u32 s63, 0x1017
	s_cbranch_scc1 .Ltk_pf_end_1
	s_lshl_b32 s4, s63, 1
	s_and_b32 s4, s4, 0x3ffc
	s_sub_i32 s4, 0x209c, s4
	s_bitcmp1_b32 s63, 0
	s_cselect_b32 s5, 0x2100, 0
	s_add_i32 s60, s4, 3
	s_lshr_b32 s60, s60, 6
	s_add_i32 s62, s2, 1
	s_cmp_gt_u32 s62, s60
	s_cbranch_scc1 .Ltk_pf_w_2
	v_readlane_b32 s64, v240, 11
	v_readlane_b32 s65, v240, 12
	s_lshl_b32 s62, s62, 6
	s_add_i32 s62, s62, s5
	v_add_lshl_u32 v0, s62, v101, 7
	s_nop 1
	global_load_dword v242, v0, s[64:65]
